# code placement: K-loop heads at byte phases 28 / 8 / 28 mod 64 (no MFMA crosses a 64-byte line, each loop spans 33 lines)
# baseline (speedup 1.0000x reference)
;     ...
;         const bool has_next = S.next(ui + 1, nxt);
;         const char* nA = has_next ? nxt.A : cA; const char* nB = has_next ? nxt.B : cB;
;         for (int t = 0; t < nt; t += 2) {
;             const bool last = (t == nt - 2);
;             const char* a1 = cA + (size_t)(t + 1) * kstep;
;             const char* a2 = last ? nA : cA + (size_t)(t + 2) * kstep; const char* b2 = last ? nB : cB + (size_t)(t + 2) * kstep;
.LBB0_158:
	s_mov_b64 s[56:57], s[18:19]
	s_mov_b64 s[16:17], s[2:3]
	v_mov_b32_e32 v228, v128
	s_xor_b64 s[2:3], s[36:37], -1
	v_mov_b32_e32 v128, s57
	s_and_b64 s[0:1], s[36:37], exec
	v_cndmask_b32_e64 v132, v189, v128, s[36:37]
	v_mov_b32_e32 v128, s56
	s_mov_b64 s[68:69], s[8:9]
	s_mov_b64 s[54:55], s[40:41]
	s_cselect_b32 s18, s17, s13
	s_cselect_b32 s19, s16, s12
	v_cndmask_b32_e64 v133, v188, v128, s[36:37]
	s_mov_b32 s8, 0
	s_mov_b64 s[0:1], 0x100
	v_mov_b64_e32 v[128:129], v[202:203]
	v_mov_b64_e32 v[130:131], v[200:201]
	s_nop 0
	s_nop 0
	s_nop 0
	s_nop 0
	s_nop 0
	s_nop 0
	s_nop 0
	s_nop 0
	s_nop 0
	s_nop 0
	s_nop 0
	s_nop 0
	s_nop 0
	s_nop 0

;     ...
;         const bool has_next = S.next(ui + 1, nxt);
;         const char* nA = has_next ? nxt.A : cA; const char* nB = has_next ? nxt.B : cB;
;         for (int t = 0; t < nt; t += 2) {
;             const bool last = (t == nt - 2);
;             const char* a1 = cA + (size_t)(t + 1) * kstep;
;             const char* a2 = last ? nA : cA + (size_t)(t + 2) * kstep; const char* b2 = last ? nB : cB + (size_t)(t + 2) * kstep;
.LBB0_415:
	s_mov_b64 s[12:13], s[18:19]
	v_mov_b32_e32 v150, v144
	s_xor_b64 s[18:19], s[16:17], -1
	v_mov_b32_e32 v144, s13
	s_mov_b64 s[68:69], s[2:3]
	s_and_b64 s[0:1], s[16:17], exec
	v_cndmask_b32_e64 v151, v129, v144, s[16:17]
	v_mov_b32_e32 v144, s12
	s_mov_b64 s[56:57], s[8:9]
	s_mov_b32 s62, s26
	s_cselect_b32 s6, s69, s53
	s_cselect_b32 s7, s68, s52
	v_cndmask_b32_e64 v152, v128, v144, s[16:17]
	s_mov_b32 s2, 0
	s_mov_b64 s[0:1], 0x100
	v_mov_b64_e32 v[144:145], v[142:143]
	v_mov_b64_e32 v[146:147], v[140:141]
	s_nop 0
	s_nop 0
	s_nop 0
	s_nop 0
	s_nop 0
	s_nop 0
